# GEMM2 epilogue stores: ds_bpermute lane transpose so the four 16-byte chunks of a row sit in consecutive lanes (64 contiguous bytes per lane group), store issued one site later
# speedup vs baseline: 1.0248x; 1.0007x over previous
.LBB0_935:
	s_add_u32 s2, s12, 0xfffc0080
	s_addc_u32 s3, s13, -1
	s_add_i32 s38, 32, 0x10000
	v_add_u32_e32 v152, s38, v145
	ds_read_b128 v[140:143], v152
	ds_read_b128 v[148:151], v152 offset:1024
	ds_read_b128 v[164:167], v152 offset:2048
	ds_read_b128 v[168:171], v152 offset:3072
	s_cmp_eq_u32 vcc_hi, 12
	s_cselect_b32 s3, s31, s3
	s_cselect_b32 s2, s4, s2
	s_cselect_b32 s19, s11, s35
	s_cselect_b32 s18, vcc_lo, s34
	s_add_i32 m0, s14, 0xc000
	ds_read_b128 v[172:175], v147
	ds_read_b128 v[176:179], v147 offset:1024
	ds_read_b128 v[182:185], v147 offset:2048
	ds_read_b128 v[186:189], v147 offset:3072
	ds_read_b128 v[190:193], v147 offset:4096
	ds_read_b128 v[194:197], v147 offset:5120
	ds_read_b128 v[198:201], v147 offset:6144
	ds_read_b128 v[202:205], v147 offset:7168
	global_load_lds_dwordx4 v136, s[12:13]
	s_add_i32 m0, s14, 0xe000
	s_nop 0
	global_load_lds_dwordx4 v138, s[12:13]
	s_waitcnt lgkmcnt(8)
	s_barrier
	s_waitcnt lgkmcnt(0)
	s_waitcnt lgkmcnt(0)
	v_mfma_f32_16x16x32_bf16 v[126:129], v[140:143], v[172:175], v[126:129]
	v_mfma_f32_16x16x32_bf16 v[122:125], v[164:167], v[172:175], v[122:125]
	v_mfma_f32_16x16x32_bf16 v[110:113], v[140:143], v[182:185], v[110:113]
	v_mfma_f32_16x16x32_bf16 v[106:109], v[164:167], v[182:185], v[106:109]
	v_mfma_f32_16x16x32_bf16 v[94:97], v[140:143], v[190:193], v[94:97]
	v_mfma_f32_16x16x32_bf16 v[90:93], v[164:167], v[190:193], v[90:93]
	v_mfma_f32_16x16x32_bf16 v[78:81], v[140:143], v[198:201], v[78:81]
	v_mfma_f32_16x16x32_bf16 v[74:77], v[164:167], v[198:201], v[74:77]
	v_mfma_f32_16x16x32_bf16 v[126:129], v[148:151], v[176:179], v[126:129]
	v_mfma_f32_16x16x32_bf16 v[122:125], v[168:171], v[176:179], v[122:125]
	v_mfma_f32_16x16x32_bf16 v[110:113], v[148:151], v[186:189], v[110:113]
	v_mfma_f32_16x16x32_bf16 v[106:109], v[168:171], v[186:189], v[106:109]
	v_mfma_f32_16x16x32_bf16 v[94:97], v[148:151], v[194:197], v[94:97]
	v_mfma_f32_16x16x32_bf16 v[90:93], v[168:171], v[194:197], v[90:93]
	v_mfma_f32_16x16x32_bf16 v[78:81], v[148:151], v[202:205], v[78:81]
	v_mfma_f32_16x16x32_bf16 v[74:77], v[168:171], v[202:205], v[74:77]
	s_barrier
	s_add_i32 s24, 32, 0x14000
	s_add_i32 s38, s38, s7
	ds_read_b128 v[206:209], v152 offset:16384
	ds_read_b128 v[210:213], v152 offset:17408
	ds_read_b128 v[214:217], v152 offset:18432
	ds_read_b128 v[218:221], v152 offset:19456
	s_mov_b32 m0, s38
	s_nop 0
	global_load_lds_dwordx4 v154, s[18:19]
	s_add_i32 m0, s38, 0x2000
	s_nop 0
	global_load_lds_dwordx4 v130, s[18:19]
	s_barrier
	s_waitcnt lgkmcnt(0)
	s_waitcnt lgkmcnt(0)
	v_mfma_f32_16x16x32_bf16 v[118:121], v[206:209], v[172:175], v[118:121]
	v_mfma_f32_16x16x32_bf16 v[114:117], v[214:217], v[172:175], v[114:117]
	v_mfma_f32_16x16x32_bf16 v[102:105], v[206:209], v[182:185], v[102:105]
	v_mfma_f32_16x16x32_bf16 v[98:101], v[214:217], v[182:185], v[98:101]
	v_mfma_f32_16x16x32_bf16 v[86:89], v[206:209], v[190:193], v[86:89]
	v_mfma_f32_16x16x32_bf16 v[82:85], v[214:217], v[190:193], v[82:85]
	v_mfma_f32_16x16x32_bf16 v[70:73], v[206:209], v[198:201], v[70:73]
	v_mfma_f32_16x16x32_bf16 v[66:69], v[214:217], v[198:201], v[66:69]
	v_mfma_f32_16x16x32_bf16 v[118:121], v[210:213], v[176:179], v[118:121]
	v_mfma_f32_16x16x32_bf16 v[114:117], v[218:221], v[176:179], v[114:117]
	v_mfma_f32_16x16x32_bf16 v[102:105], v[210:213], v[186:189], v[102:105]
	v_mfma_f32_16x16x32_bf16 v[98:101], v[218:221], v[186:189], v[98:101]
	v_mfma_f32_16x16x32_bf16 v[86:89], v[210:213], v[194:197], v[86:89]
	v_mfma_f32_16x16x32_bf16 v[82:85], v[218:221], v[194:197], v[82:85]
	v_mfma_f32_16x16x32_bf16 v[70:73], v[210:213], v[202:205], v[70:73]
	v_mfma_f32_16x16x32_bf16 v[66:69], v[218:221], v[202:205], v[66:69]
	s_mov_b32 m0, s14
	s_mov_b64 s[98:99], s[2:3]
	s_barrier
	ds_read_b128 v[172:175], v147 offset:16384
	ds_read_b128 v[176:179], v147 offset:17408
	ds_read_b128 v[182:185], v147 offset:18432
	ds_read_b128 v[186:189], v147 offset:19456
	ds_read_b128 v[190:193], v147 offset:20480
	ds_read_b128 v[194:197], v147 offset:21504
	ds_read_b128 v[198:201], v147 offset:22528
	ds_read_b128 v[202:205], v147 offset:23552
	global_load_lds_dwordx4 v134, s[2:3]
	s_mov_b32 m0, s20
	s_nop 0
	global_load_lds_dwordx4 v132, s[2:3]
	s_barrier
	s_waitcnt lgkmcnt(0)
	s_waitcnt lgkmcnt(0)
	v_mfma_f32_16x16x32_bf16 v[62:65], v[140:143], v[172:175], v[62:65]
	v_mfma_f32_16x16x32_bf16 v[58:61], v[164:167], v[172:175], v[58:61]
	v_mfma_f32_16x16x32_bf16 v[46:49], v[140:143], v[182:185], v[46:49]
	v_mfma_f32_16x16x32_bf16 v[42:45], v[164:167], v[182:185], v[42:45]
	v_mfma_f32_16x16x32_bf16 v[30:33], v[140:143], v[190:193], v[30:33]
	v_mfma_f32_16x16x32_bf16 v[26:29], v[164:167], v[190:193], v[26:29]
	v_mfma_f32_16x16x32_bf16 v[14:17], v[140:143], v[198:201], v[14:17]
	v_mfma_f32_16x16x32_bf16 v[10:13], v[164:167], v[198:201], v[10:13]
	v_mfma_f32_16x16x32_bf16 v[62:65], v[148:151], v[176:179], v[62:65]
	v_mfma_f32_16x16x32_bf16 v[58:61], v[168:171], v[176:179], v[58:61]
	v_mfma_f32_16x16x32_bf16 v[46:49], v[148:151], v[186:189], v[46:49]
	v_mfma_f32_16x16x32_bf16 v[42:45], v[168:171], v[186:189], v[42:45]
	v_mfma_f32_16x16x32_bf16 v[30:33], v[148:151], v[194:197], v[30:33]
	v_mfma_f32_16x16x32_bf16 v[26:29], v[168:171], v[194:197], v[26:29]
	v_mfma_f32_16x16x32_bf16 v[14:17], v[148:151], v[202:205], v[14:17]
	v_mfma_f32_16x16x32_bf16 v[10:13], v[168:171], v[202:205], v[10:13]
	s_barrier
	s_add_u32 s38, s18, 0x40000
	s_addc_u32 s39, s19, 0
	s_add_i32 s24, s24, s7
	s_mov_b32 m0, s24
	s_nop 0
	global_load_lds_dwordx4 v154, s[38:39]
	s_add_i32 m0, s24, 0x2000
	s_nop 0
	global_load_lds_dwordx4 v130, s[38:39]
	s_waitcnt vmcnt(6)
	s_barrier
	v_mfma_f32_16x16x32_bf16 v[54:57], v[206:209], v[172:175], v[54:57]
	v_mfma_f32_16x16x32_bf16 v[50:53], v[214:217], v[172:175], v[50:53]
	v_mfma_f32_16x16x32_bf16 v[38:41], v[206:209], v[182:185], v[38:41]
	v_mfma_f32_16x16x32_bf16 v[34:37], v[214:217], v[182:185], v[34:37]
	v_mfma_f32_16x16x32_bf16 v[22:25], v[206:209], v[190:193], v[22:25]
	v_mfma_f32_16x16x32_bf16 v[18:21], v[214:217], v[190:193], v[18:21]
	v_mfma_f32_16x16x32_bf16 v[6:9], v[206:209], v[198:201], v[6:9]
	v_mfma_f32_16x16x32_bf16 v[2:5], v[214:217], v[198:201], v[2:5]
	v_mfma_f32_16x16x32_bf16 v[54:57], v[210:213], v[176:179], v[54:57]
	v_mfma_f32_16x16x32_bf16 v[50:53], v[218:221], v[176:179], v[50:53]
	v_mfma_f32_16x16x32_bf16 v[38:41], v[210:213], v[186:189], v[38:41]
	v_mfma_f32_16x16x32_bf16 v[34:37], v[218:221], v[186:189], v[34:37]
	v_mfma_f32_16x16x32_bf16 v[22:25], v[210:213], v[194:197], v[22:25]
	v_mfma_f32_16x16x32_bf16 v[18:21], v[218:221], v[194:197], v[18:21]
	v_mfma_f32_16x16x32_bf16 v[6:9], v[210:213], v[202:205], v[6:9]
	v_mfma_f32_16x16x32_bf16 v[2:5], v[218:221], v[202:205], v[2:5]
	s_add_i32 s24, 32, 0x18000
	s_barrier
	ds_read_b128 v[140:143], v152 offset:32768
	ds_read_b128 v[148:151], v152 offset:33792
	ds_read_b128 v[164:167], v152 offset:34816
	ds_read_b128 v[168:171], v152 offset:35840
	s_add_u32 s2, s2, 0x40000
	s_addc_u32 s3, s3, 0
	s_mov_b32 m0, s21
	ds_read_b128 v[172:175], v147 offset:32768
	ds_read_b128 v[176:179], v147 offset:33792
	ds_read_b128 v[182:185], v147 offset:34816
	ds_read_b128 v[186:189], v147 offset:35840
	ds_read_b128 v[190:193], v147 offset:36864
	ds_read_b128 v[194:197], v147 offset:37888
	ds_read_b128 v[198:201], v147 offset:38912
	ds_read_b128 v[202:205], v147 offset:39936
	global_load_lds_dwordx4 v134, s[2:3]
	s_mov_b32 m0, s22
	s_nop 0
	global_load_lds_dwordx4 v132, s[2:3]
	s_waitcnt lgkmcnt(8)
	s_barrier
	s_waitcnt lgkmcnt(0)
	s_waitcnt lgkmcnt(0)
	v_mfma_f32_16x16x32_bf16 v[126:129], v[140:143], v[172:175], v[126:129]
	v_mfma_f32_16x16x32_bf16 v[122:125], v[164:167], v[172:175], v[122:125]
	v_mfma_f32_16x16x32_bf16 v[110:113], v[140:143], v[182:185], v[110:113]
	v_mfma_f32_16x16x32_bf16 v[106:109], v[164:167], v[182:185], v[106:109]
	v_mfma_f32_16x16x32_bf16 v[94:97], v[140:143], v[190:193], v[94:97]
	v_mfma_f32_16x16x32_bf16 v[90:93], v[164:167], v[190:193], v[90:93]
	v_mfma_f32_16x16x32_bf16 v[78:81], v[140:143], v[198:201], v[78:81]
	v_mfma_f32_16x16x32_bf16 v[74:77], v[164:167], v[198:201], v[74:77]
	v_mfma_f32_16x16x32_bf16 v[126:129], v[148:151], v[176:179], v[126:129]
	v_mfma_f32_16x16x32_bf16 v[122:125], v[168:171], v[176:179], v[122:125]
	v_mfma_f32_16x16x32_bf16 v[110:113], v[148:151], v[186:189], v[110:113]
	v_mfma_f32_16x16x32_bf16 v[106:109], v[168:171], v[186:189], v[106:109]
	v_mfma_f32_16x16x32_bf16 v[94:97], v[148:151], v[194:197], v[94:97]
	v_mfma_f32_16x16x32_bf16 v[90:93], v[168:171], v[194:197], v[90:93]
	v_mfma_f32_16x16x32_bf16 v[78:81], v[148:151], v[202:205], v[78:81]
	v_mfma_f32_16x16x32_bf16 v[74:77], v[168:171], v[202:205], v[74:77]
	s_barrier
	s_add_i32 s38, 32, 0x1c000
	s_add_i32 s2, s24, s7
	s_mov_b32 m0, s2
	ds_read_b128 v[206:209], v152 offset:49152
	ds_read_b128 v[210:213], v152 offset:50176
	ds_read_b128 v[214:217], v152 offset:51200
	ds_read_b128 v[218:221], v152 offset:52224
	s_add_u32 s100, s18, 128
	s_addc_u32 s101, s19, 0
	global_load_lds_dwordx4 v154, s[100:101]
	s_add_i32 m0, s2, 0x2000
	s_nop 0
	global_load_lds_dwordx4 v130, s[100:101]
	s_barrier
	s_waitcnt lgkmcnt(0)
	s_waitcnt lgkmcnt(0)
	v_mfma_f32_16x16x32_bf16 v[118:121], v[206:209], v[172:175], v[118:121]
	v_mfma_f32_16x16x32_bf16 v[114:117], v[214:217], v[172:175], v[114:117]
	v_mfma_f32_16x16x32_bf16 v[102:105], v[206:209], v[182:185], v[102:105]
	v_mfma_f32_16x16x32_bf16 v[98:101], v[214:217], v[182:185], v[98:101]
	v_mfma_f32_16x16x32_bf16 v[86:89], v[206:209], v[190:193], v[86:89]
	v_mfma_f32_16x16x32_bf16 v[82:85], v[214:217], v[190:193], v[82:85]
	v_mfma_f32_16x16x32_bf16 v[70:73], v[206:209], v[198:201], v[70:73]
	v_mfma_f32_16x16x32_bf16 v[66:69], v[214:217], v[198:201], v[66:69]
	v_mfma_f32_16x16x32_bf16 v[118:121], v[210:213], v[176:179], v[118:121]
	v_mfma_f32_16x16x32_bf16 v[114:117], v[218:221], v[176:179], v[114:117]
	v_mfma_f32_16x16x32_bf16 v[102:105], v[210:213], v[186:189], v[102:105]
	v_mfma_f32_16x16x32_bf16 v[98:101], v[218:221], v[186:189], v[98:101]
	v_mfma_f32_16x16x32_bf16 v[86:89], v[210:213], v[194:197], v[86:89]
	v_mfma_f32_16x16x32_bf16 v[82:85], v[218:221], v[194:197], v[82:85]
	v_mfma_f32_16x16x32_bf16 v[70:73], v[210:213], v[202:205], v[70:73]
	v_mfma_f32_16x16x32_bf16 v[66:69], v[218:221], v[202:205], v[66:69]
	s_mov_b32 m0, s23
	s_barrier
	ds_read_b128 v[172:175], v147 offset:49152
	ds_read_b128 v[176:179], v147 offset:50176
	ds_read_b128 v[182:185], v147 offset:51200
	ds_read_b128 v[186:189], v147 offset:52224
	ds_read_b128 v[190:193], v147 offset:53248
	ds_read_b128 v[194:197], v147 offset:54272
	ds_read_b128 v[198:201], v147 offset:55296
	ds_read_b128 v[202:205], v147 offset:56320
	s_add_u32 s98, s98, 128
	s_addc_u32 s99, s99, 0
	global_load_lds_dwordx4 v134, s[98:99]
	s_mov_b32 m0, s28
	s_nop 0
	global_load_lds_dwordx4 v132, s[98:99]
	s_barrier
	s_waitcnt lgkmcnt(0)
	s_waitcnt lgkmcnt(0)
	v_mfma_f32_16x16x32_bf16 v[62:65], v[140:143], v[172:175], v[62:65]
	v_mfma_f32_16x16x32_bf16 v[58:61], v[164:167], v[172:175], v[58:61]
	v_mfma_f32_16x16x32_bf16 v[46:49], v[140:143], v[182:185], v[46:49]
	v_mfma_f32_16x16x32_bf16 v[42:45], v[164:167], v[182:185], v[42:45]
	v_mfma_f32_16x16x32_bf16 v[30:33], v[140:143], v[190:193], v[30:33]
	v_mfma_f32_16x16x32_bf16 v[26:29], v[164:167], v[190:193], v[26:29]
	v_mfma_f32_16x16x32_bf16 v[14:17], v[140:143], v[198:201], v[14:17]
	v_mfma_f32_16x16x32_bf16 v[10:13], v[164:167], v[198:201], v[10:13]
	v_mfma_f32_16x16x32_bf16 v[62:65], v[148:151], v[176:179], v[62:65]
	v_mfma_f32_16x16x32_bf16 v[58:61], v[168:171], v[176:179], v[58:61]
	v_mfma_f32_16x16x32_bf16 v[46:49], v[148:151], v[186:189], v[46:49]
	v_mfma_f32_16x16x32_bf16 v[42:45], v[168:171], v[186:189], v[42:45]
	v_mfma_f32_16x16x32_bf16 v[30:33], v[148:151], v[194:197], v[30:33]
	v_mfma_f32_16x16x32_bf16 v[26:29], v[168:171], v[194:197], v[26:29]
	v_mfma_f32_16x16x32_bf16 v[14:17], v[148:151], v[202:205], v[14:17]
	v_mfma_f32_16x16x32_bf16 v[10:13], v[168:171], v[202:205], v[10:13]
	s_barrier
	s_add_u32 s2, s18, 0x40080
	s_addc_u32 s3, s19, 0
	s_add_i32 s18, s38, s7
	s_mov_b32 m0, s18
	s_nop 0
	global_load_lds_dwordx4 v154, s[2:3]
	s_add_i32 m0, s18, 0x2000
	s_nop 0
	global_load_lds_dwordx4 v130, s[2:3]
	s_waitcnt vmcnt(6)
	s_barrier
	v_mfma_f32_16x16x32_bf16 v[54:57], v[206:209], v[172:175], v[54:57]
	v_mfma_f32_16x16x32_bf16 v[50:53], v[214:217], v[172:175], v[50:53]
	v_mfma_f32_16x16x32_bf16 v[38:41], v[206:209], v[182:185], v[38:41]
	v_mfma_f32_16x16x32_bf16 v[34:37], v[214:217], v[182:185], v[34:37]
	v_mfma_f32_16x16x32_bf16 v[22:25], v[206:209], v[190:193], v[22:25]
	v_mfma_f32_16x16x32_bf16 v[18:21], v[214:217], v[190:193], v[18:21]
	v_mfma_f32_16x16x32_bf16 v[6:9], v[206:209], v[198:201], v[6:9]
	v_mfma_f32_16x16x32_bf16 v[2:5], v[214:217], v[198:201], v[2:5]
	v_mfma_f32_16x16x32_bf16 v[54:57], v[210:213], v[176:179], v[54:57]
	v_mfma_f32_16x16x32_bf16 v[50:53], v[218:221], v[176:179], v[50:53]
	v_mfma_f32_16x16x32_bf16 v[38:41], v[210:213], v[186:189], v[38:41]
	v_mfma_f32_16x16x32_bf16 v[34:37], v[218:221], v[186:189], v[34:37]
	v_mfma_f32_16x16x32_bf16 v[22:25], v[210:213], v[194:197], v[22:25]
	v_mfma_f32_16x16x32_bf16 v[18:21], v[218:221], v[194:197], v[18:21]
	v_mfma_f32_16x16x32_bf16 v[6:9], v[210:213], v[202:205], v[6:9]
	v_mfma_f32_16x16x32_bf16 v[2:5], v[218:221], v[202:205], v[2:5]
	s_add_i32 vcc_hi, vcc_hi, 2
	s_add_u32 s12, s12, 0x100
	s_addc_u32 s13, s13, 0
	s_add_u32 s34, s34, 0x100
	s_addc_u32 s35, s35, 0
	s_cmp_gt_u32 vcc_hi, 13
	s_barrier
	s_cbranch_scc0 .LBB0_935
	v_lshl_add_u32 v142, s36, 8, v144
	v_ashrrev_i32_e32 v143, 31, v142
	v_lshl_or_b32 v140, s37, 8, v146
	v_lshlrev_b64 v[150:151], 11, v[142:143]
	v_ashrrev_i32_e32 v141, 31, v140
	v_lshl_add_u64 v[150:151], s[58:59], 0, v[150:151]
	v_lshl_add_u64 v[164:165], v[140:141], 1, v[150:151]
	v_mov_b64_e32 v[238:239], v[164:165]
	global_load_dwordx4 v[150:153], v[164:165], off
	s_nop 0
	global_load_dwordx4 v[164:167], v[164:165], off offset:256
	v_add_co_u32_e32 v240, vcc, 0x8000, v238
	s_nop 1
	v_addc_co_u32_e32 v241, vcc, 0, v239, vcc
	global_load_dwordx4 v[182:185], v[240:241], off
	global_load_dwordx4 v[186:189], v[240:241], off offset:256
	v_add_co_u32_e32 v240, vcc, 0x10000, v238
	s_nop 1
	v_addc_co_u32_e32 v241, vcc, 0, v239, vcc
	global_load_dwordx4 v[190:193], v[240:241], off
	global_load_dwordx4 v[194:197], v[240:241], off offset:256
	v_add_co_u32_e32 v240, vcc, 0x18000, v238
	s_nop 1
	v_addc_co_u32_e32 v241, vcc, 0, v239, vcc
	global_load_dwordx4 v[198:201], v[240:241], off
	global_load_dwordx4 v[202:205], v[240:241], off offset:256
	v_add_co_u32_e32 v240, vcc, 0x40000, v238
	s_nop 1
	v_addc_co_u32_e32 v241, vcc, 0, v239, vcc
	global_load_dwordx4 v[206:209], v[240:241], off
	global_load_dwordx4 v[210:213], v[240:241], off offset:256
	v_add_co_u32_e32 v240, vcc, 0x48000, v238
	s_nop 1
	v_addc_co_u32_e32 v241, vcc, 0, v239, vcc
	global_load_dwordx4 v[214:217], v[240:241], off
	global_load_dwordx4 v[218:221], v[240:241], off offset:256
	v_add_co_u32_e32 v240, vcc, 0x50000, v238
	s_nop 1
	v_addc_co_u32_e32 v241, vcc, 0, v239, vcc
	global_load_dwordx4 v[222:225], v[240:241], off
	global_load_dwordx4 v[226:229], v[240:241], off offset:256
	v_add_co_u32_e32 v240, vcc, 0x58000, v238
	s_nop 1
	v_addc_co_u32_e32 v241, vcc, 0, v239, vcc
	global_load_dwordx4 v[230:233], v[240:241], off
	global_load_dwordx4 v[234:237], v[240:241], off offset:256
	v_lshlrev_b32_e32 v148, 1, v140
	s_waitcnt vmcnt(14)
	v_lshlrev_b32_e32 v149, 16, v150
	v_lshlrev_b32_e32 v171, 16, v164
	v_and_b32_e32 v164, 0xffff0000, v164
	v_and_b32_e32 v150, 0xffff0000, v150
	v_lshlrev_b32_e32 v168, 16, v151
	v_and_b32_e32 v151, 0xffff0000, v151
	v_lshlrev_b32_e32 v173, 16, v166
	v_and_b32_e32 v166, 0xffff0000, v166
	v_lshlrev_b32_e32 v174, 16, v167
	v_and_b32_e32 v167, 0xffff0000, v167
	v_add_f32_e32 v118, v118, v171
	v_add_f32_e32 v119, v119, v164
	v_lshlrev_b32_e32 v172, 16, v165
	v_add_f32_e32 v126, v126, v149
	v_add_f32_e32 v149, v114, v173
	v_add_f32_e32 v114, v127, v150
	v_add_f32_e32 v127, v115, v166
	v_add_f32_e32 v115, v128, v168
	v_add_f32_e32 v128, v116, v174
	v_add_f32_e32 v116, v129, v151
	v_add_f32_e32 v129, v117, v167
	v_mul_f32_e32 v117, v118, v118
	v_mul_f32_e32 v150, v119, v119
	v_add_f32_e32 v120, v120, v172
	v_fmac_f32_e32 v117, v126, v126
	v_fmac_f32_e32 v150, v114, v114
	v_and_b32_e32 v165, 0xffff0000, v165
	v_add_f32_e32 v117, v117, v150
	v_mul_f32_e32 v150, v120, v120
	v_add_f32_e32 v121, v121, v165
	v_fmac_f32_e32 v150, v115, v115
	v_add_f32_e32 v117, v150, v117
	v_mul_f32_e32 v150, v121, v121
	v_lshlrev_b32_e32 v169, 16, v152
	v_fmac_f32_e32 v150, v116, v116
	v_add_f32_e32 v122, v122, v169
	v_add_f32_e32 v117, v150, v117
	v_mul_f32_e32 v150, v149, v149
	v_and_b32_e32 v152, 0xffff0000, v152
	v_fmac_f32_e32 v150, v122, v122
	v_add_f32_e32 v123, v123, v152
	v_add_f32_e32 v117, v150, v117
	v_mul_f32_e32 v150, v127, v127
	v_lshlrev_b32_e32 v170, 16, v153
	v_fmac_f32_e32 v150, v123, v123
	v_add_f32_e32 v124, v124, v170
	v_add_f32_e32 v117, v150, v117
	v_mul_f32_e32 v150, v128, v128
	v_and_b32_e32 v153, 0xffff0000, v153
	v_fmac_f32_e32 v150, v124, v124
	v_add_f32_e32 v125, v125, v153
	v_add_f32_e32 v117, v150, v117
	v_mul_f32_e32 v150, v129, v129
	v_fmac_f32_e32 v150, v125, v125
	v_lshl_add_u32 v151, v142, 11, v148
	v_cvt_pk_bf16_f32 v114, v126, v114
	v_cvt_pk_bf16_f32 v115, v115, v116
	v_add_f32_e32 v150, v150, v117
	v_cvt_pk_bf16_f32 v116, v122, v123
	v_cvt_pk_bf16_f32 v117, v124, v125
	v_and_b32_e32 v245, 3, v0
	v_bfe_u32 v246, v0, 2, 4
	v_lshl_add_u32 v247, v245, 4, v246
	v_lshlrev_b32_e32 v247, 2, v247
	v_and_b32_e32 v252, 15, v0
	v_sub_u32_e32 v246, v246, v252
	v_lshlrev_b32_e32 v246, 11, v246
	v_bfe_u32 v252, v0, 4, 2
	v_sub_u32_e32 v245, v245, v252
	v_lshl_add_u32 v246, v245, 4, v246
	v_mov_b32_e32 v245, v247
	v_add_u32_e32 v247, v246, v151
	ds_bpermute_b32 v252, v245, v114
	ds_bpermute_b32 v253, v245, v115
	ds_bpermute_b32 v254, v245, v116
	ds_bpermute_b32 v255, v245, v117
	s_nop 1
	v_cvt_pk_bf16_f32 v114, v118, v119
	v_cvt_pk_bf16_f32 v115, v120, v121
	v_cvt_pk_bf16_f32 v116, v149, v127
	v_cvt_pk_bf16_f32 v117, v128, v129
	s_waitcnt lgkmcnt(0)
	buffer_store_dwordx4 v[252:255], v247, s[64:67], 0 offen sc1
	v_add_u32_e32 v247, v246, v151
	ds_bpermute_b32 v252, v245, v114
	ds_bpermute_b32 v253, v245, v115
	ds_bpermute_b32 v254, v245, v116
	ds_bpermute_b32 v255, v245, v117
	s_nop 1
	v_and_b32_e32 v115, 64, v181
	v_xor_b32_e32 v114, 16, v181
	v_add_u32_e32 v115, 64, v115
	v_cmp_lt_i32_e32 vcc, v114, v115
	v_xor_b32_e32 v117, 32, v181
	s_nop 0
	v_cndmask_b32_e32 v114, v181, v114, vcc
	v_lshlrev_b32_e32 v116, 2, v114
	ds_bpermute_b32 v114, v116, v150
	v_cmp_lt_i32_e32 vcc, v117, v115
	s_waitcnt lgkmcnt(0)
	v_add_f32_e32 v114, v150, v114
	v_cndmask_b32_e32 v115, v181, v117, vcc
	v_lshlrev_b32_e32 v117, 2, v115
	ds_bpermute_b32 v115, v117, v114
	s_and_saveexec_b64 s[2:3], s[40:41]
	s_cbranch_execz .LBB0_938
	v_lshl_add_u64 v[118:119], v[142:143], 2, s[0:1]
	s_waitcnt lgkmcnt(0)
	v_add_f32_e32 v114, v114, v115
	global_atomic_add_f32 v[118:119], v114, off
.LBB0_938:
	s_or_b64 exec, exec, s[2:3]
	v_or_b32_e32 v114, 16, v142
	s_waitcnt lgkmcnt(0)
	v_ashrrev_i32_e32 v115, 31, v114
	v_lshlrev_b64 v[118:119], 11, v[114:115]
	v_lshl_add_u64 v[118:119], s[58:59], 0, v[118:119]
	v_lshl_add_u64 v[122:123], v[140:141], 1, v[118:119]
	s_waitcnt vmcnt(15)
	v_mov_b64_e32 v[118:119], v[182:183]
	v_mov_b64_e32 v[120:121], v[184:185]
	s_nop 0
	v_mov_b64_e32 v[122:123], v[186:187]
	v_mov_b64_e32 v[124:125], v[188:189]
	v_lshlrev_b32_e32 v126, 16, v118
	v_and_b32_e32 v118, 0xffff0000, v118
	v_lshlrev_b32_e32 v143, 16, v122
	v_and_b32_e32 v122, 0xffff0000, v122
	v_lshlrev_b32_e32 v127, 16, v119
	v_lshlrev_b32_e32 v128, 16, v120
	v_lshlrev_b32_e32 v150, 16, v124
	v_lshlrev_b32_e32 v151, 16, v125
	v_add_f32_e32 v110, v110, v126
	v_add_f32_e32 v126, v102, v143
	v_add_f32_e32 v102, v111, v118
	v_add_f32_e32 v111, v103, v122
	v_lshlrev_b32_e32 v149, 16, v123
	v_add_f32_e32 v106, v106, v128
	v_add_f32_e32 v128, v98, v150
	v_add_f32_e32 v103, v112, v127
	v_add_f32_e32 v112, v100, v151
	v_mul_f32_e32 v98, v126, v126
	v_mul_f32_e32 v100, v111, v111
	v_add_f32_e32 v104, v104, v149
	v_fmac_f32_e32 v98, v110, v110
	v_fmac_f32_e32 v100, v102, v102
	v_and_b32_e32 v123, 0xffff0000, v123
	v_add_f32_e32 v98, v98, v100
	v_mul_f32_e32 v100, v104, v104
	v_and_b32_e32 v119, 0xffff0000, v119
	v_add_f32_e32 v105, v105, v123
	v_fmac_f32_e32 v100, v103, v103
	v_add_f32_e32 v113, v113, v119
	v_add_f32_e32 v98, v100, v98
	v_mul_f32_e32 v100, v105, v105
	v_fmac_f32_e32 v100, v113, v113
	v_and_b32_e32 v124, 0xffff0000, v124
	v_add_f32_e32 v98, v100, v98
	v_mul_f32_e32 v100, v128, v128
	v_and_b32_e32 v120, 0xffff0000, v120
	v_add_f32_e32 v99, v99, v124
	v_fmac_f32_e32 v100, v106, v106
	v_add_f32_e32 v107, v107, v120
	v_add_f32_e32 v98, v100, v98
	v_mul_f32_e32 v100, v99, v99
	v_lshlrev_b32_e32 v129, 16, v121
	v_fmac_f32_e32 v100, v107, v107
	v_and_b32_e32 v125, 0xffff0000, v125
	v_add_f32_e32 v108, v108, v129
	v_add_f32_e32 v98, v100, v98
	v_mul_f32_e32 v100, v112, v112
	v_and_b32_e32 v121, 0xffff0000, v121
	v_add_f32_e32 v118, v101, v125
	v_fmac_f32_e32 v100, v108, v108
	v_add_f32_e32 v109, v109, v121
	v_add_f32_e32 v98, v100, v98
	v_mul_f32_e32 v100, v118, v118
	v_fmac_f32_e32 v100, v109, v109
	v_add_f32_e32 v98, v100, v98
	v_lshl_add_u32 v119, v114, 11, v148
	v_cvt_pk_bf16_f32 v100, v110, v102
	v_cvt_pk_bf16_f32 v101, v103, v113
	v_cvt_pk_bf16_f32 v102, v106, v107
	v_cvt_pk_bf16_f32 v103, v108, v109
	s_waitcnt lgkmcnt(0)
	buffer_store_dwordx4 v[252:255], v247, s[64:67], 0 offen offset:256 sc1
	v_add_u32_e32 v247, v246, v119
	ds_bpermute_b32 v252, v245, v100
	ds_bpermute_b32 v253, v245, v101
	ds_bpermute_b32 v254, v245, v102
	ds_bpermute_b32 v255, v245, v103
	s_nop 1
	v_cvt_pk_bf16_f32 v100, v126, v111
	v_cvt_pk_bf16_f32 v101, v104, v105
	v_cvt_pk_bf16_f32 v102, v128, v99
	ds_bpermute_b32 v99, v116, v98
	v_cvt_pk_bf16_f32 v103, v112, v118
	s_waitcnt lgkmcnt(0)
	buffer_store_dwordx4 v[252:255], v247, s[64:67], 0 offen sc1
	v_add_u32_e32 v247, v246, v119
	ds_bpermute_b32 v252, v245, v100
	ds_bpermute_b32 v253, v245, v101
	ds_bpermute_b32 v254, v245, v102
	ds_bpermute_b32 v255, v245, v103
	s_waitcnt lgkmcnt(0)
	v_add_f32_e32 v98, v98, v99
	ds_bpermute_b32 v99, v117, v98
	s_and_saveexec_b64 s[2:3], s[40:41]
	s_cbranch_execz .LBB0_940
	v_lshl_add_u64 v[100:101], v[114:115], 2, s[0:1]
	s_waitcnt lgkmcnt(0)
	v_add_f32_e32 v98, v98, v99
	global_atomic_add_f32 v[100:101], v98, off
.LBB0_940:
	s_or_b64 exec, exec, s[2:3]
	v_or_b32_e32 v98, 32, v142
	s_waitcnt lgkmcnt(0)
	v_ashrrev_i32_e32 v99, 31, v98
	v_lshlrev_b64 v[100:101], 11, v[98:99]
	v_lshl_add_u64 v[100:101], s[58:59], 0, v[100:101]
	v_lshl_add_u64 v[104:105], v[140:141], 1, v[100:101]
	s_waitcnt vmcnt(16)
	v_mov_b64_e32 v[100:101], v[190:191]
	v_mov_b64_e32 v[102:103], v[192:193]
	s_nop 0
	v_mov_b64_e32 v[104:105], v[194:195]
	v_mov_b64_e32 v[106:107], v[196:197]
	v_lshlrev_b32_e32 v108, 16, v100
	v_and_b32_e32 v100, 0xffff0000, v100
	v_lshlrev_b32_e32 v112, 16, v104
	v_and_b32_e32 v104, 0xffff0000, v104
	v_lshlrev_b32_e32 v109, 16, v101
	v_lshlrev_b32_e32 v110, 16, v102
	v_lshlrev_b32_e32 v114, 16, v106
	v_lshlrev_b32_e32 v115, 16, v107
	v_add_f32_e32 v94, v94, v108
	v_add_f32_e32 v108, v86, v112
	v_add_f32_e32 v86, v95, v100
	v_add_f32_e32 v95, v87, v104
	v_lshlrev_b32_e32 v113, 16, v105
	v_add_f32_e32 v90, v90, v110
	v_add_f32_e32 v110, v82, v114
	v_add_f32_e32 v87, v96, v109
	v_add_f32_e32 v96, v84, v115
	v_mul_f32_e32 v82, v108, v108
	v_mul_f32_e32 v84, v95, v95
	v_add_f32_e32 v88, v88, v113
	v_fmac_f32_e32 v82, v94, v94
	v_fmac_f32_e32 v84, v86, v86
	v_and_b32_e32 v105, 0xffff0000, v105
	v_add_f32_e32 v82, v82, v84
	v_mul_f32_e32 v84, v88, v88
	v_and_b32_e32 v101, 0xffff0000, v101
	v_add_f32_e32 v89, v89, v105
	v_fmac_f32_e32 v84, v87, v87
	v_add_f32_e32 v97, v97, v101
	v_add_f32_e32 v82, v84, v82
	v_mul_f32_e32 v84, v89, v89
	v_fmac_f32_e32 v84, v97, v97
	v_and_b32_e32 v106, 0xffff0000, v106
	v_add_f32_e32 v82, v84, v82
	v_mul_f32_e32 v84, v110, v110
	v_and_b32_e32 v102, 0xffff0000, v102
	v_add_f32_e32 v83, v83, v106
	v_fmac_f32_e32 v84, v90, v90
	v_add_f32_e32 v91, v91, v102
	v_add_f32_e32 v82, v84, v82
	v_mul_f32_e32 v84, v83, v83
	v_lshlrev_b32_e32 v111, 16, v103
	v_fmac_f32_e32 v84, v91, v91
	v_and_b32_e32 v107, 0xffff0000, v107
	v_add_f32_e32 v92, v92, v111
	v_add_f32_e32 v82, v84, v82
	v_mul_f32_e32 v84, v96, v96
	v_and_b32_e32 v103, 0xffff0000, v103
	v_add_f32_e32 v100, v85, v107
	v_fmac_f32_e32 v84, v92, v92
	v_add_f32_e32 v93, v93, v103
	v_add_f32_e32 v82, v84, v82
	v_mul_f32_e32 v84, v100, v100
	v_fmac_f32_e32 v84, v93, v93
	v_add_f32_e32 v82, v84, v82
	v_lshl_add_u32 v101, v98, 11, v148
	v_cvt_pk_bf16_f32 v84, v94, v86
	v_cvt_pk_bf16_f32 v85, v87, v97
	v_cvt_pk_bf16_f32 v86, v90, v91
	v_cvt_pk_bf16_f32 v87, v92, v93
	s_waitcnt lgkmcnt(0)
	buffer_store_dwordx4 v[252:255], v247, s[64:67], 0 offen offset:256 sc1
	v_add_u32_e32 v247, v246, v101
	ds_bpermute_b32 v252, v245, v84
	ds_bpermute_b32 v253, v245, v85
	ds_bpermute_b32 v254, v245, v86
	ds_bpermute_b32 v255, v245, v87
	s_nop 1
	v_cvt_pk_bf16_f32 v84, v108, v95
	v_cvt_pk_bf16_f32 v85, v88, v89
	v_cvt_pk_bf16_f32 v86, v110, v83
	ds_bpermute_b32 v83, v116, v82
	v_cvt_pk_bf16_f32 v87, v96, v100
	s_waitcnt lgkmcnt(0)
	buffer_store_dwordx4 v[252:255], v247, s[64:67], 0 offen sc1
	v_add_u32_e32 v247, v246, v101
	ds_bpermute_b32 v252, v245, v84
	ds_bpermute_b32 v253, v245, v85
	ds_bpermute_b32 v254, v245, v86
	ds_bpermute_b32 v255, v245, v87
	s_waitcnt lgkmcnt(0)
	v_add_f32_e32 v82, v82, v83
	ds_bpermute_b32 v83, v117, v82
	s_and_saveexec_b64 s[2:3], s[40:41]
	s_cbranch_execz .LBB0_942
	v_lshl_add_u64 v[84:85], v[98:99], 2, s[0:1]
	s_waitcnt lgkmcnt(0)
	v_add_f32_e32 v82, v82, v83
	global_atomic_add_f32 v[84:85], v82, off
.LBB0_942:
	s_or_b64 exec, exec, s[2:3]
	v_or_b32_e32 v82, 48, v142
	s_waitcnt lgkmcnt(0)
	v_ashrrev_i32_e32 v83, 31, v82
	v_lshlrev_b64 v[84:85], 11, v[82:83]
	v_lshl_add_u64 v[84:85], s[58:59], 0, v[84:85]
	v_lshl_add_u64 v[88:89], v[140:141], 1, v[84:85]
	s_waitcnt vmcnt(17)
	v_mov_b64_e32 v[84:85], v[198:199]
	v_mov_b64_e32 v[86:87], v[200:201]
	s_nop 0
	v_mov_b64_e32 v[88:89], v[202:203]
	v_mov_b64_e32 v[90:91], v[204:205]
	v_lshlrev_b32_e32 v92, 16, v84
	v_and_b32_e32 v84, 0xffff0000, v84
	v_lshlrev_b32_e32 v96, 16, v88
	v_and_b32_e32 v88, 0xffff0000, v88
	v_lshlrev_b32_e32 v93, 16, v85
	v_lshlrev_b32_e32 v94, 16, v86
	v_lshlrev_b32_e32 v98, 16, v90
	v_lshlrev_b32_e32 v99, 16, v91
	v_add_f32_e32 v78, v78, v92
	v_add_f32_e32 v92, v70, v96
	v_add_f32_e32 v70, v79, v84
	v_add_f32_e32 v79, v71, v88
	v_lshlrev_b32_e32 v97, 16, v89
	v_add_f32_e32 v74, v74, v94
	v_add_f32_e32 v94, v66, v98
	v_add_f32_e32 v71, v80, v93
	v_add_f32_e32 v80, v68, v99
	v_mul_f32_e32 v66, v92, v92
	v_mul_f32_e32 v68, v79, v79
	v_add_f32_e32 v72, v72, v97
	v_fmac_f32_e32 v66, v78, v78
	v_fmac_f32_e32 v68, v70, v70
	v_and_b32_e32 v89, 0xffff0000, v89
	v_add_f32_e32 v66, v66, v68
	v_mul_f32_e32 v68, v72, v72
	v_and_b32_e32 v85, 0xffff0000, v85
	v_add_f32_e32 v73, v73, v89
	v_fmac_f32_e32 v68, v71, v71
	v_add_f32_e32 v81, v81, v85
	v_add_f32_e32 v66, v68, v66
	v_mul_f32_e32 v68, v73, v73
	v_fmac_f32_e32 v68, v81, v81
	v_and_b32_e32 v90, 0xffff0000, v90
	v_add_f32_e32 v66, v68, v66
	v_mul_f32_e32 v68, v94, v94
	v_and_b32_e32 v86, 0xffff0000, v86
	v_add_f32_e32 v67, v67, v90
	v_fmac_f32_e32 v68, v74, v74
	v_add_f32_e32 v75, v75, v86
	v_add_f32_e32 v66, v68, v66
	v_mul_f32_e32 v68, v67, v67
	v_lshlrev_b32_e32 v95, 16, v87
	v_fmac_f32_e32 v68, v75, v75
	v_and_b32_e32 v91, 0xffff0000, v91
	v_add_f32_e32 v76, v76, v95
	v_add_f32_e32 v66, v68, v66
	v_mul_f32_e32 v68, v80, v80
	v_and_b32_e32 v87, 0xffff0000, v87
	v_add_f32_e32 v84, v69, v91
	v_fmac_f32_e32 v68, v76, v76
	v_add_f32_e32 v77, v77, v87
	v_add_f32_e32 v66, v68, v66
	v_mul_f32_e32 v68, v84, v84
	v_fmac_f32_e32 v68, v77, v77
	v_add_f32_e32 v66, v68, v66
	v_lshl_add_u32 v85, v82, 11, v148
	v_cvt_pk_bf16_f32 v68, v78, v70
	v_cvt_pk_bf16_f32 v69, v71, v81
	v_cvt_pk_bf16_f32 v70, v74, v75
	v_cvt_pk_bf16_f32 v71, v76, v77
	s_waitcnt lgkmcnt(0)
	buffer_store_dwordx4 v[252:255], v247, s[64:67], 0 offen offset:256 sc1
	v_add_u32_e32 v247, v246, v85
	ds_bpermute_b32 v252, v245, v68
	ds_bpermute_b32 v253, v245, v69
	ds_bpermute_b32 v254, v245, v70
	ds_bpermute_b32 v255, v245, v71
	s_nop 1
	v_cvt_pk_bf16_f32 v68, v92, v79
	v_cvt_pk_bf16_f32 v69, v72, v73
	v_cvt_pk_bf16_f32 v70, v94, v67
	ds_bpermute_b32 v67, v116, v66
	v_cvt_pk_bf16_f32 v71, v80, v84
	s_waitcnt lgkmcnt(0)
	buffer_store_dwordx4 v[252:255], v247, s[64:67], 0 offen sc1
	v_add_u32_e32 v247, v246, v85
	ds_bpermute_b32 v252, v245, v68
	ds_bpermute_b32 v253, v245, v69
	ds_bpermute_b32 v254, v245, v70
	ds_bpermute_b32 v255, v245, v71
	s_waitcnt lgkmcnt(0)
	v_add_f32_e32 v66, v66, v67
	ds_bpermute_b32 v67, v117, v66
	s_and_saveexec_b64 s[2:3], s[40:41]
	v_readlane_b32 s24, v244, 11
	v_readlane_b32 s18, v242, 47
	v_readlane_b32 s19, v242, 48
	s_cbranch_execz .LBB0_944
	v_lshl_add_u64 v[68:69], v[82:83], 2, s[0:1]
	s_waitcnt lgkmcnt(0)
	v_add_f32_e32 v66, v66, v67
	global_atomic_add_f32 v[68:69], v66, off
.LBB0_944:
	s_or_b64 exec, exec, s[2:3]
	v_add_u32_e32 v66, 0x80, v142
	s_waitcnt lgkmcnt(0)
	v_ashrrev_i32_e32 v67, 31, v66
	v_lshlrev_b64 v[68:69], 11, v[66:67]
	v_lshl_add_u64 v[68:69], s[58:59], 0, v[68:69]
	v_lshl_add_u64 v[72:73], v[140:141], 1, v[68:69]
	s_waitcnt vmcnt(18)
	v_mov_b64_e32 v[68:69], v[206:207]
	v_mov_b64_e32 v[70:71], v[208:209]
	s_nop 0
	v_mov_b64_e32 v[72:73], v[210:211]
	v_mov_b64_e32 v[74:75], v[212:213]
	v_lshlrev_b32_e32 v76, 16, v68
	v_and_b32_e32 v68, 0xffff0000, v68
	v_lshlrev_b32_e32 v80, 16, v72
	v_and_b32_e32 v72, 0xffff0000, v72
	v_lshlrev_b32_e32 v77, 16, v69
	v_lshlrev_b32_e32 v78, 16, v70
	v_lshlrev_b32_e32 v82, 16, v74
	v_lshlrev_b32_e32 v83, 16, v75
	v_add_f32_e32 v62, v62, v76
	v_add_f32_e32 v76, v54, v80
	v_add_f32_e32 v54, v63, v68
	v_add_f32_e32 v63, v55, v72
	v_lshlrev_b32_e32 v81, 16, v73
	v_add_f32_e32 v58, v58, v78
	v_add_f32_e32 v78, v50, v82
	v_add_f32_e32 v55, v64, v77
	v_add_f32_e32 v64, v52, v83
	v_mul_f32_e32 v50, v76, v76
	v_mul_f32_e32 v52, v63, v63
	v_add_f32_e32 v56, v56, v81
	v_fmac_f32_e32 v50, v62, v62
	v_fmac_f32_e32 v52, v54, v54
	v_and_b32_e32 v73, 0xffff0000, v73
	v_add_f32_e32 v50, v50, v52
	v_mul_f32_e32 v52, v56, v56
	v_and_b32_e32 v69, 0xffff0000, v69
	v_add_f32_e32 v57, v57, v73
	v_fmac_f32_e32 v52, v55, v55
	v_add_f32_e32 v65, v65, v69
	v_add_f32_e32 v50, v52, v50
	v_mul_f32_e32 v52, v57, v57
	v_fmac_f32_e32 v52, v65, v65
	v_and_b32_e32 v74, 0xffff0000, v74
	v_add_f32_e32 v50, v52, v50
	v_mul_f32_e32 v52, v78, v78
	v_and_b32_e32 v70, 0xffff0000, v70
	v_add_f32_e32 v51, v51, v74
	v_fmac_f32_e32 v52, v58, v58
	v_add_f32_e32 v59, v59, v70
	v_add_f32_e32 v50, v52, v50
	v_mul_f32_e32 v52, v51, v51
	v_lshlrev_b32_e32 v79, 16, v71
	v_fmac_f32_e32 v52, v59, v59
	v_and_b32_e32 v75, 0xffff0000, v75
	v_add_f32_e32 v60, v60, v79
	v_add_f32_e32 v50, v52, v50
	v_mul_f32_e32 v52, v64, v64
	v_and_b32_e32 v71, 0xffff0000, v71
	v_add_f32_e32 v68, v53, v75
	v_fmac_f32_e32 v52, v60, v60
	v_add_f32_e32 v61, v61, v71
	v_add_f32_e32 v50, v52, v50
	v_mul_f32_e32 v52, v68, v68
	v_fmac_f32_e32 v52, v61, v61
	v_add_f32_e32 v50, v52, v50
	v_lshl_add_u32 v69, v66, 11, v148
	v_cvt_pk_bf16_f32 v52, v62, v54
	v_cvt_pk_bf16_f32 v53, v55, v65
	v_cvt_pk_bf16_f32 v54, v58, v59
	v_cvt_pk_bf16_f32 v55, v60, v61
	s_waitcnt lgkmcnt(0)
	buffer_store_dwordx4 v[252:255], v247, s[64:67], 0 offen offset:256 sc1
	v_add_u32_e32 v247, v246, v69
	ds_bpermute_b32 v252, v245, v52
	ds_bpermute_b32 v253, v245, v53
	ds_bpermute_b32 v254, v245, v54
	ds_bpermute_b32 v255, v245, v55
	s_nop 1
	v_cvt_pk_bf16_f32 v52, v76, v63
	v_cvt_pk_bf16_f32 v53, v56, v57
	v_cvt_pk_bf16_f32 v54, v78, v51
	ds_bpermute_b32 v51, v116, v50
	v_cvt_pk_bf16_f32 v55, v64, v68
	s_waitcnt lgkmcnt(0)
	buffer_store_dwordx4 v[252:255], v247, s[64:67], 0 offen sc1
	v_add_u32_e32 v247, v246, v69
	ds_bpermute_b32 v252, v245, v52
	ds_bpermute_b32 v253, v245, v53
	ds_bpermute_b32 v254, v245, v54
	ds_bpermute_b32 v255, v245, v55
	s_waitcnt lgkmcnt(0)
	v_add_f32_e32 v50, v50, v51
	ds_bpermute_b32 v51, v117, v50
	s_and_saveexec_b64 s[2:3], s[40:41]
	s_cbranch_execz .LBB0_946
	v_lshl_add_u64 v[52:53], v[66:67], 2, s[0:1]
	s_waitcnt lgkmcnt(0)
	v_add_f32_e32 v50, v50, v51
	global_atomic_add_f32 v[52:53], v50, off
.LBB0_946:
	s_or_b64 exec, exec, s[2:3]
	v_add_u32_e32 v50, 0x90, v142
	s_waitcnt lgkmcnt(0)
	v_ashrrev_i32_e32 v51, 31, v50
	v_lshlrev_b64 v[52:53], 11, v[50:51]
	v_lshl_add_u64 v[52:53], s[58:59], 0, v[52:53]
	v_lshl_add_u64 v[56:57], v[140:141], 1, v[52:53]
	s_waitcnt vmcnt(19)
	v_mov_b64_e32 v[52:53], v[214:215]
	v_mov_b64_e32 v[54:55], v[216:217]
	s_nop 0
	v_mov_b64_e32 v[56:57], v[218:219]
	v_mov_b64_e32 v[58:59], v[220:221]
	v_lshlrev_b32_e32 v60, 16, v52
	v_and_b32_e32 v52, 0xffff0000, v52
	v_lshlrev_b32_e32 v64, 16, v56
	v_and_b32_e32 v56, 0xffff0000, v56
	v_lshlrev_b32_e32 v61, 16, v53
	v_lshlrev_b32_e32 v62, 16, v54
	v_lshlrev_b32_e32 v66, 16, v58
	v_lshlrev_b32_e32 v67, 16, v59
	v_add_f32_e32 v46, v46, v60
	v_add_f32_e32 v60, v38, v64
	v_add_f32_e32 v38, v47, v52
	v_add_f32_e32 v47, v39, v56
	v_lshlrev_b32_e32 v65, 16, v57
	v_add_f32_e32 v42, v42, v62
	v_add_f32_e32 v62, v34, v66
	v_add_f32_e32 v39, v48, v61
	v_add_f32_e32 v48, v36, v67
	v_mul_f32_e32 v34, v60, v60
	v_mul_f32_e32 v36, v47, v47
	v_add_f32_e32 v40, v40, v65
	v_fmac_f32_e32 v34, v46, v46
	v_fmac_f32_e32 v36, v38, v38
	v_and_b32_e32 v57, 0xffff0000, v57
	v_add_f32_e32 v34, v34, v36
	v_mul_f32_e32 v36, v40, v40
	v_and_b32_e32 v53, 0xffff0000, v53
	v_add_f32_e32 v41, v41, v57
	v_fmac_f32_e32 v36, v39, v39
	v_add_f32_e32 v49, v49, v53
	v_add_f32_e32 v34, v36, v34
	v_mul_f32_e32 v36, v41, v41
	v_fmac_f32_e32 v36, v49, v49
	v_and_b32_e32 v58, 0xffff0000, v58
	v_add_f32_e32 v34, v36, v34
	v_mul_f32_e32 v36, v62, v62
	v_and_b32_e32 v54, 0xffff0000, v54
	v_add_f32_e32 v35, v35, v58
	v_fmac_f32_e32 v36, v42, v42
	v_add_f32_e32 v43, v43, v54
	v_add_f32_e32 v34, v36, v34
	v_mul_f32_e32 v36, v35, v35
	v_lshlrev_b32_e32 v63, 16, v55
	v_fmac_f32_e32 v36, v43, v43
	v_and_b32_e32 v59, 0xffff0000, v59
	v_add_f32_e32 v44, v44, v63
	v_add_f32_e32 v34, v36, v34
	v_mul_f32_e32 v36, v48, v48
	v_and_b32_e32 v55, 0xffff0000, v55
	v_add_f32_e32 v52, v37, v59
	v_fmac_f32_e32 v36, v44, v44
	v_add_f32_e32 v45, v45, v55
	v_add_f32_e32 v34, v36, v34
	v_mul_f32_e32 v36, v52, v52
	v_fmac_f32_e32 v36, v45, v45
	v_add_f32_e32 v34, v36, v34
	v_lshl_add_u32 v53, v50, 11, v148
	v_cvt_pk_bf16_f32 v36, v46, v38
	v_cvt_pk_bf16_f32 v37, v39, v49
	v_cvt_pk_bf16_f32 v38, v42, v43
	v_cvt_pk_bf16_f32 v39, v44, v45
	s_waitcnt lgkmcnt(0)
	buffer_store_dwordx4 v[252:255], v247, s[64:67], 0 offen offset:256 sc1
	v_add_u32_e32 v247, v246, v53
	ds_bpermute_b32 v252, v245, v36
	ds_bpermute_b32 v253, v245, v37
	ds_bpermute_b32 v254, v245, v38
	ds_bpermute_b32 v255, v245, v39
	s_nop 1
	v_cvt_pk_bf16_f32 v36, v60, v47
	v_cvt_pk_bf16_f32 v37, v40, v41
	v_cvt_pk_bf16_f32 v38, v62, v35
	ds_bpermute_b32 v35, v116, v34
	v_cvt_pk_bf16_f32 v39, v48, v52
	s_waitcnt lgkmcnt(0)
	buffer_store_dwordx4 v[252:255], v247, s[64:67], 0 offen sc1
	v_add_u32_e32 v247, v246, v53
	ds_bpermute_b32 v252, v245, v36
	ds_bpermute_b32 v253, v245, v37
	ds_bpermute_b32 v254, v245, v38
	ds_bpermute_b32 v255, v245, v39
	s_waitcnt lgkmcnt(0)
	v_add_f32_e32 v34, v34, v35
	ds_bpermute_b32 v35, v117, v34
	s_and_saveexec_b64 s[2:3], s[40:41]
	s_cbranch_execz .LBB0_948
	v_lshl_add_u64 v[36:37], v[50:51], 2, s[0:1]
	s_waitcnt lgkmcnt(0)
	v_add_f32_e32 v34, v34, v35
	global_atomic_add_f32 v[36:37], v34, off
.LBB0_948:
	s_or_b64 exec, exec, s[2:3]
	v_add_u32_e32 v34, 0xa0, v142
	s_waitcnt lgkmcnt(0)
	v_ashrrev_i32_e32 v35, 31, v34
	v_lshlrev_b64 v[36:37], 11, v[34:35]
	v_lshl_add_u64 v[36:37], s[58:59], 0, v[36:37]
	v_lshl_add_u64 v[40:41], v[140:141], 1, v[36:37]
	s_waitcnt vmcnt(20)
	v_mov_b64_e32 v[36:37], v[222:223]
	v_mov_b64_e32 v[38:39], v[224:225]
	s_nop 0
	v_mov_b64_e32 v[40:41], v[226:227]
	v_mov_b64_e32 v[42:43], v[228:229]
	v_lshlrev_b32_e32 v44, 16, v36
	v_and_b32_e32 v36, 0xffff0000, v36
	v_lshlrev_b32_e32 v48, 16, v40
	v_and_b32_e32 v40, 0xffff0000, v40
	v_lshlrev_b32_e32 v45, 16, v37
	v_lshlrev_b32_e32 v46, 16, v38
	v_lshlrev_b32_e32 v50, 16, v42
	v_lshlrev_b32_e32 v51, 16, v43
	v_add_f32_e32 v30, v30, v44
	v_add_f32_e32 v44, v22, v48
	v_add_f32_e32 v22, v31, v36
	v_add_f32_e32 v31, v23, v40
	v_lshlrev_b32_e32 v49, 16, v41
	v_add_f32_e32 v26, v26, v46
	v_add_f32_e32 v46, v18, v50
	v_add_f32_e32 v23, v32, v45
	v_add_f32_e32 v32, v20, v51
	v_mul_f32_e32 v18, v44, v44
	v_mul_f32_e32 v20, v31, v31
	v_add_f32_e32 v24, v24, v49
	v_fmac_f32_e32 v18, v30, v30
	v_fmac_f32_e32 v20, v22, v22
	v_and_b32_e32 v41, 0xffff0000, v41
	v_add_f32_e32 v18, v18, v20
	v_mul_f32_e32 v20, v24, v24
	v_and_b32_e32 v37, 0xffff0000, v37
	v_add_f32_e32 v25, v25, v41
	v_fmac_f32_e32 v20, v23, v23
	v_add_f32_e32 v33, v33, v37
	v_add_f32_e32 v18, v20, v18
	v_mul_f32_e32 v20, v25, v25
	v_fmac_f32_e32 v20, v33, v33
	v_and_b32_e32 v42, 0xffff0000, v42
	v_add_f32_e32 v18, v20, v18
	v_mul_f32_e32 v20, v46, v46
	v_and_b32_e32 v38, 0xffff0000, v38
	v_add_f32_e32 v19, v19, v42
	v_fmac_f32_e32 v20, v26, v26
	v_add_f32_e32 v27, v27, v38
	v_add_f32_e32 v18, v20, v18
	v_mul_f32_e32 v20, v19, v19
	v_lshlrev_b32_e32 v47, 16, v39
	v_fmac_f32_e32 v20, v27, v27
	v_and_b32_e32 v43, 0xffff0000, v43
	v_add_f32_e32 v28, v28, v47
	v_add_f32_e32 v18, v20, v18
	v_mul_f32_e32 v20, v32, v32
	v_and_b32_e32 v39, 0xffff0000, v39
	v_add_f32_e32 v36, v21, v43
	v_fmac_f32_e32 v20, v28, v28
	v_add_f32_e32 v29, v29, v39
	v_add_f32_e32 v18, v20, v18
	v_mul_f32_e32 v20, v36, v36
	v_fmac_f32_e32 v20, v29, v29
	v_add_f32_e32 v18, v20, v18
	v_lshl_add_u32 v37, v34, 11, v148
	v_cvt_pk_bf16_f32 v20, v30, v22
	v_cvt_pk_bf16_f32 v21, v23, v33
	v_cvt_pk_bf16_f32 v22, v26, v27
	v_cvt_pk_bf16_f32 v23, v28, v29
	s_waitcnt lgkmcnt(0)
	buffer_store_dwordx4 v[252:255], v247, s[64:67], 0 offen offset:256 sc1
	v_add_u32_e32 v247, v246, v37
	ds_bpermute_b32 v252, v245, v20
	ds_bpermute_b32 v253, v245, v21
	ds_bpermute_b32 v254, v245, v22
	ds_bpermute_b32 v255, v245, v23
	s_nop 1
	v_cvt_pk_bf16_f32 v20, v44, v31
	v_cvt_pk_bf16_f32 v21, v24, v25
	v_cvt_pk_bf16_f32 v22, v46, v19
	ds_bpermute_b32 v19, v116, v18
	v_cvt_pk_bf16_f32 v23, v32, v36
	s_waitcnt lgkmcnt(0)
	buffer_store_dwordx4 v[252:255], v247, s[64:67], 0 offen sc1
	v_add_u32_e32 v247, v246, v37
	ds_bpermute_b32 v252, v245, v20
	ds_bpermute_b32 v253, v245, v21
	ds_bpermute_b32 v254, v245, v22
	ds_bpermute_b32 v255, v245, v23
	s_waitcnt lgkmcnt(0)
	v_add_f32_e32 v18, v18, v19
	ds_bpermute_b32 v19, v117, v18
	s_and_saveexec_b64 s[2:3], s[40:41]
	s_cbranch_execz .LBB0_950
	v_lshl_add_u64 v[20:21], v[34:35], 2, s[0:1]
	s_waitcnt lgkmcnt(0)
	v_add_f32_e32 v18, v18, v19
	global_atomic_add_f32 v[20:21], v18, off
.LBB0_950:
	s_or_b64 exec, exec, s[2:3]
	v_add_u32_e32 v18, 0xb0, v142
	s_waitcnt lgkmcnt(0)
	v_ashrrev_i32_e32 v19, 31, v18
	v_lshlrev_b64 v[20:21], 11, v[18:19]
	v_lshl_add_u64 v[20:21], s[58:59], 0, v[20:21]
	v_lshl_add_u64 v[24:25], v[140:141], 1, v[20:21]
	s_waitcnt vmcnt(21)
	v_mov_b64_e32 v[20:21], v[230:231]
	v_mov_b64_e32 v[22:23], v[232:233]
	s_nop 0
	v_mov_b64_e32 v[24:25], v[234:235]
	v_mov_b64_e32 v[26:27], v[236:237]
	v_lshl_add_u32 v28, v18, 11, v148
	v_lshlrev_b32_e32 v29, 16, v20
	v_lshlrev_b32_e32 v33, 16, v24
	v_and_b32_e32 v24, 0xffff0000, v24
	v_and_b32_e32 v20, 0xffff0000, v20
	v_lshlrev_b32_e32 v30, 16, v21
	v_and_b32_e32 v21, 0xffff0000, v21
	v_lshlrev_b32_e32 v34, 16, v25
	v_lshlrev_b32_e32 v35, 16, v26
	v_and_b32_e32 v26, 0xffff0000, v26
	v_lshlrev_b32_e32 v36, 16, v27
	v_and_b32_e32 v27, 0xffff0000, v27
	v_add_f32_e32 v6, v6, v33
	v_add_f32_e32 v7, v7, v24
	v_lshlrev_b32_e32 v31, 16, v22
	v_and_b32_e32 v22, 0xffff0000, v22
	v_and_b32_e32 v25, 0xffff0000, v25
	v_add_f32_e32 v14, v14, v29
	v_add_f32_e32 v15, v15, v20
	v_add_f32_e32 v20, v3, v26
	v_add_f32_e32 v3, v16, v30
	v_add_f32_e32 v8, v8, v34
	v_add_f32_e32 v16, v4, v36
	v_add_f32_e32 v4, v17, v21
	v_add_f32_e32 v17, v5, v27
	v_mul_f32_e32 v5, v6, v6
	v_mul_f32_e32 v21, v7, v7
	v_lshlrev_b32_e32 v32, 16, v23
	v_and_b32_e32 v23, 0xffff0000, v23
	v_add_f32_e32 v11, v11, v22
	v_add_f32_e32 v9, v9, v25
	v_mul_f32_e32 v22, v8, v8
	v_fmac_f32_e32 v5, v14, v14
	v_fmac_f32_e32 v21, v15, v15
	v_add_f32_e32 v29, v2, v35
	v_add_f32_e32 v13, v13, v23
	v_mul_f32_e32 v23, v9, v9
	v_fmac_f32_e32 v22, v3, v3
	v_add_f32_e32 v5, v5, v21
	v_add_f32_e32 v10, v10, v31
	v_mul_f32_e32 v24, v29, v29
	v_fmac_f32_e32 v23, v4, v4
	v_add_f32_e32 v5, v22, v5
	v_mul_f32_e32 v25, v20, v20
	v_fmac_f32_e32 v24, v10, v10
	v_add_f32_e32 v5, v23, v5
	v_add_f32_e32 v12, v12, v32
	v_mul_f32_e32 v26, v16, v16
	v_fmac_f32_e32 v25, v11, v11
	v_add_f32_e32 v5, v24, v5
	v_mul_f32_e32 v27, v17, v17
	v_fmac_f32_e32 v26, v12, v12
	v_add_f32_e32 v5, v25, v5
	v_fmac_f32_e32 v27, v13, v13
	v_add_f32_e32 v5, v26, v5
	v_cvt_pk_bf16_f32 v2, v14, v15
	v_add_f32_e32 v14, v27, v5
	ds_bpermute_b32 v15, v116, v14
	v_cvt_pk_bf16_f32 v3, v3, v4
	v_cvt_pk_bf16_f32 v4, v10, v11
	v_cvt_pk_bf16_f32 v5, v12, v13
	s_waitcnt lgkmcnt(0)
	buffer_store_dwordx4 v[252:255], v247, s[64:67], 0 offen offset:256 sc1
	v_add_u32_e32 v247, v246, v28
	ds_bpermute_b32 v252, v245, v2
	ds_bpermute_b32 v253, v245, v3
	ds_bpermute_b32 v254, v245, v4
	ds_bpermute_b32 v255, v245, v5
	s_waitcnt lgkmcnt(0)
	s_nop 0
	v_add_f32_e32 v2, v14, v15
	ds_bpermute_b32 v3, v117, v2
	v_cvt_pk_bf16_f32 v4, v6, v7
	v_cvt_pk_bf16_f32 v5, v8, v9
	v_cvt_pk_bf16_f32 v6, v29, v20
	v_cvt_pk_bf16_f32 v7, v16, v17
	s_waitcnt lgkmcnt(0)
	buffer_store_dwordx4 v[252:255], v247, s[64:67], 0 offen sc1
	v_add_u32_e32 v247, v246, v28
	ds_bpermute_b32 v252, v245, v4
	ds_bpermute_b32 v253, v245, v5
	ds_bpermute_b32 v254, v245, v6
	ds_bpermute_b32 v255, v245, v7
	s_waitcnt lgkmcnt(0)
	buffer_store_dwordx4 v[252:255], v247, s[64:67], 0 offen offset:256 sc1
	s_and_saveexec_b64 s[2:3], s[40:41]
	s_cbranch_execz .LBB0_927
	v_lshl_add_u64 v[4:5], v[18:19], 2, s[0:1]
	s_waitcnt lgkmcnt(0)
	v_add_f32_e32 v2, v2, v3
	global_atomic_add_f32 v[4:5], v2, off
	s_branch .LBB0_927
